# MLA L0: triple-buffered K/V, DMA two tiles ahead, address block + DMA issue inside first score chain; MLA L1: DMA two tiles ahead only
# baseline (speedup 1.0000x reference)
.LBB0_2311:
	s_ashr_i32 s14, s33, 9
	s_ashr_i32 s15, s14, 31
	s_lshl_b32 s0, s33, 8
	s_lshl_b64 s[8:9], s[14:15], 14
	s_and_b32 s0, s0, 0x3f00
	s_or_b32 s8, s8, s0
	s_lshl_b32 s0, s14, 8
	s_add_i32 s0, s0, 0x8000
	s_mul_i32 s4, s9, 0xc00
	s_mul_hi_u32 s12, s8, 0xc00
	s_bfe_u32 s36, s33, 0x30006
	s_ashr_i32 s1, s0, 31
	s_add_i32 s12, s12, s4
	s_mul_i32 s4, s8, 0xc00
	v_readlane_b32 s28, v242, 21
	v_readlane_b32 s29, v242, 22
	s_add_u32 s4, s28, s4
	s_addc_u32 s12, s29, s12
	s_mul_i32 s21, s36, 0x180
	s_add_u32 s28, s4, s21
	s_addc_u32 s29, s12, 0
	s_mul_i32 s12, s0, 0xc00
	s_mul_hi_i32 s4, s0, 0xc00
	s_add_u32 s12, s24, s12
	s_addc_u32 s4, s25, s4
	s_add_u32 s12, s12, s21
	s_addc_u32 s13, s4, 0
	s_mul_i32 s35, s14, 0x3000000
	s_mul_hi_i32 s4, s14, 0x3000000
	s_add_u32 s35, s24, s35
	s_addc_u32 s4, s25, s4
	s_add_u32 s38, s35, s21
	s_addc_u32 s39, s4, 0
	s_lshl_b64 s[0:1], s[0:1], 12
	s_add_u32 s0, s31, s0
	s_addc_u32 s1, s34, s1
	s_lshl_b32 s4, s36, 9
	s_add_u32 s0, s0, s4
	s_addc_u32 s1, s1, 0
	s_add_u32 s44, s0, 0x100
	s_addc_u32 s45, s1, 0
	s_lshl_b64 s[14:15], s[14:15], 26
	s_add_u32 s14, s31, s14
	s_addc_u32 s15, s34, s15
	s_add_u32 s4, s14, s4
	s_addc_u32 s14, s15, 0
	s_add_u32 s46, s4, 0x100
	v_readfirstlane_b32 s52, v0
	s_addc_u32 s47, s14, 0
	s_lshr_b32 s37, s52, 6
	s_lshl_b32 s35, s37, 5
	v_or_b32_e32 v4, s35, v165
	v_mov_b64_e32 v[2:3], s[28:29]
	v_mad_u64_u32 v[2:3], s[14:15], v4, s19, v[2:3]
	s_andn2_b32 s52, s52, 63
	v_lshl_add_u64 v[2:3], v[2:3], 0, v[148:149]
	global_load_dwordx4 v[142:145], v[2:3], off
	global_load_dwordx4 v[138:141], v[2:3], off offset:32
	global_load_dwordx4 v[134:137], v[2:3], off offset:64
	global_load_dwordx4 v[130:133], v[2:3], off offset:96
	global_load_dwordx4 v[126:129], v[2:3], off offset:128
	global_load_dwordx4 v[122:125], v[2:3], off offset:160
	global_load_dwordx4 v[118:121], v[2:3], off offset:192
	global_load_dwordx4 v[114:117], v[2:3], off offset:224
	global_load_dwordx4 v[110:113], v[2:3], off offset:256
	global_load_dwordx4 v[106:109], v[2:3], off offset:288
	global_load_dwordx4 v[102:105], v[2:3], off offset:320
	global_load_dwordx4 v[98:101], v[2:3], off offset:352
	v_or_b32_e32 v2, s52, v166
	v_mul_hi_i32 v3, v2, s20
	v_lshrrev_b32_e32 v4, 31, v3
	v_ashrrev_i32_e32 v3, 2, v3
	v_add_u32_e32 v3, v3, v4
	v_mul_lo_u32 v4, v3, 24
	v_sub_u32_e32 v4, v2, v4
	v_mul_lo_u32 v5, v3, s22
	v_lshrrev_b32_e32 v3, 1, v3
	v_bitop3_b32 v3, v3, v4, 7 bitop3:0x6c
	v_lshl_add_u32 v160, v3, 3, v5
	v_add_u32_e32 v3, 0x200, v2
	v_mul_hi_i32 v4, v3, s20
	v_lshrrev_b32_e32 v5, 31, v4
	v_ashrrev_i32_e32 v4, 2, v4
	v_add_u32_e32 v4, v4, v5
	v_mul_lo_u32 v5, v4, 24
	v_sub_u32_e32 v3, v3, v5
	v_mul_lo_u32 v5, v4, s22
	v_lshrrev_b32_e32 v4, 1, v4
	v_bitop3_b32 v3, v4, v3, 7 bitop3:0x6c
	v_lshl_add_u32 v162, v3, 3, v5
	v_add_u32_e32 v3, 0x400, v2
	v_mul_hi_i32 v4, v3, s20
	v_lshrrev_b32_e32 v5, 31, v4
	v_ashrrev_i32_e32 v4, 2, v4
	v_add_u32_e32 v4, v4, v5
	s_ashr_i32 s4, s52, 4
	v_mul_lo_u32 v5, v4, 24
	s_and_b32 s14, s4, 0x1ffff0
	s_lshr_b32 s4, s4, 1
	v_sub_u32_e32 v3, v3, v5
	v_mul_lo_u32 v5, v4, s22
	v_lshrrev_b32_e32 v4, 1, v4
	s_and_b32 s4, s4, 4
	v_bitop3_b32 v3, v4, v3, 7 bitop3:0x6c
	s_or_b32 s4, s14, s4
	v_lshl_add_u32 v168, v3, 3, v5
	v_or_b32_e32 v3, s4, v178
	s_add_i32 s4, s52, 0x200
	s_ashr_i32 s4, s4, 4
	s_and_b32 s14, s4, 0x1ffff0
	s_lshr_b32 s4, s4, 1
	s_and_b32 s4, s4, 4
	v_and_or_b32 v2, v2, s16, v177
	s_or_b32 s4, s14, s4
	v_lshl_or_b32 v170, v3, 11, v2
	v_or_b32_e32 v3, s4, v178
	s_lshl_b32 s4, s37, 10
	s_add_i32 s53, s4, 0
	v_ashrrev_i32_e32 v161, 31, v160
	v_lshl_or_b32 v172, v3, 11, v2
	s_add_i32 m0, s53, 0x8000
	v_lshl_add_u64 v[2:3], v[160:161], 1, s[12:13]
	v_ashrrev_i32_e32 v163, 31, v162
	global_load_lds_dwordx4 v[2:3], off
	v_lshl_add_u64 v[2:3], v[162:163], 1, s[12:13]
	s_add_i32 m0, s53, 0xa000
	v_ashrrev_i32_e32 v169, 31, v168
	global_load_lds_dwordx4 v[2:3], off
	v_lshl_add_u64 v[2:3], v[168:169], 1, s[12:13]
	s_add_i32 m0, s53, 0xc000
	v_ashrrev_i32_e32 v171, 31, v170
	global_load_lds_dwordx4 v[2:3], off
	v_lshl_add_u64 v[2:3], v[170:171], 1, s[0:1]
	v_lshl_add_u64 v[2:3], v[2:3], 0, s[6:7]
	s_mov_b32 m0, s53
	v_ashrrev_i32_e32 v173, 31, v172
	global_load_lds_dwordx4 v[2:3], off
	v_lshl_add_u64 v[2:3], v[172:173], 1, s[0:1]
	v_lshl_add_u64 v[2:3], v[2:3], 0, s[6:7]
	s_add_i32 m0, s53, 0x2000
	s_mov_b32 s4, -2
	global_load_lds_dwordx4 v[2:3], off
	s_waitcnt vmcnt(0)
	s_mov_b64 s[0:1], 0x80
	v_mov_b32_e32 v151, 0
	v_mov_b32_e32 v2, 0
	v_mov_b32_e32 v3, v147
	v_mov_b32_e32 v4, v147
	v_mov_b32_e32 v5, v147
	v_mov_b32_e32 v6, v147
	v_mov_b32_e32 v7, v147
	v_mov_b32_e32 v8, v147
	v_mov_b32_e32 v9, v147
	v_mov_b32_e32 v10, v147
	v_mov_b32_e32 v11, v147
	v_mov_b32_e32 v12, v147
	v_mov_b32_e32 v13, v147
	v_mov_b32_e32 v14, v147
	v_mov_b32_e32 v15, v147
	v_mov_b32_e32 v16, v147
	v_mov_b32_e32 v17, v147
	v_mov_b32_e32 v18, 0
	v_mov_b32_e32 v19, v147
	v_mov_b32_e32 v20, v147
	v_mov_b32_e32 v21, v147
	v_mov_b32_e32 v22, v147
	v_mov_b32_e32 v23, v147
	v_mov_b32_e32 v24, v147
	v_mov_b32_e32 v25, v147
	v_mov_b32_e32 v26, v147
	v_mov_b32_e32 v27, v147
	v_mov_b32_e32 v28, v147
	v_mov_b32_e32 v29, v147
	v_mov_b32_e32 v30, v147
	v_mov_b32_e32 v31, v147
	v_mov_b32_e32 v32, v147
	v_mov_b32_e32 v33, v147
	v_mov_b32_e32 v34, 0
	v_mov_b32_e32 v35, v147
	v_mov_b32_e32 v36, v147
	v_mov_b32_e32 v37, v147
	v_mov_b32_e32 v38, v147
	v_mov_b32_e32 v39, v147
	v_mov_b32_e32 v40, v147
	v_mov_b32_e32 v41, v147
	v_mov_b32_e32 v42, v147
	v_mov_b32_e32 v43, v147
	v_mov_b32_e32 v44, v147
	v_mov_b32_e32 v45, v147
	v_mov_b32_e32 v46, v147
	v_mov_b32_e32 v47, v147
	v_mov_b32_e32 v48, v147
	v_mov_b32_e32 v49, v147
	v_mov_b32_e32 v50, 0
	v_mov_b32_e32 v51, v147
	v_mov_b32_e32 v52, v147
	v_mov_b32_e32 v53, v147
	v_mov_b32_e32 v54, v147
	v_mov_b32_e32 v55, v147
	v_mov_b32_e32 v56, v147
	v_mov_b32_e32 v57, v147
	v_mov_b32_e32 v58, v147
	v_mov_b32_e32 v59, v147
	v_mov_b32_e32 v60, v147
	v_mov_b32_e32 v61, v147
	v_mov_b32_e32 v62, v147
	v_mov_b32_e32 v63, v147
	v_mov_b32_e32 v64, v147
	v_mov_b32_e32 v65, v147
	s_waitcnt vmcnt(0) lgkmcnt(0)
	s_barrier
	s_mov_b32 s98, 0
	s_mov_b32 s99, 0x4000
	s_mov_b32 s101, 0x1a000
	s_mov_b32 s100, 0
	s_add_u32 s40, s12, 0x30000
	s_addc_u32 s41, s13, 0
	s_add_u32 s14, s44, 0x40000
	s_addc_u32 s15, s45, 0
	s_add_i32 s42, s53, 0x6000
	s_add_i32 s29, s53, 0x4000
	s_add_i32 m0, s42, 0x8000
	v_lshl_add_u64 v[66:67], v[160:161], 1, s[40:41]
	global_load_lds_dwordx4 v[66:67], off
	s_add_i32 m0, s42, 0xa000
	v_lshl_add_u64 v[68:69], v[162:163], 1, s[40:41]
	global_load_lds_dwordx4 v[68:69], off
	s_add_i32 m0, s42, 0xc000
	v_lshl_add_u64 v[66:67], v[168:169], 1, s[40:41]
	global_load_lds_dwordx4 v[66:67], off
	s_mov_b32 m0, s29
	v_lshl_add_u64 v[68:69], v[170:171], 1, s[14:15]
	global_load_lds_dwordx4 v[68:69], off
	s_add_i32 m0, s29, 0x2000
	v_lshl_add_u64 v[66:67], v[172:173], 1, s[14:15]
	global_load_lds_dwordx4 v[66:67], off
.LBB0_2312:
	v_add_co_u32_e64 v66, s[14:15], s4, 2
	s_nop 0
	s_lshl_b64 s[28:29], s[4:5], 6
	s_and_b64 s[40:41], s[14:15], exec
	s_cselect_b32 s29, s1, s29
	s_cselect_b32 s28, s0, s28
	s_mul_i32 s42, s29, 0xc00
	s_mul_hi_u32 s43, s28, 0xc00
	s_cselect_b32 s41, s13, s39
	s_cselect_b32 s40, s12, s38
	s_add_i32 s43, s43, s42
	s_mul_i32 s42, s28, 0xc00
	s_add_u32 s40, s40, s42
	s_addc_u32 s41, s41, s43
	s_add_i32 s42, s100, 2
	s_add_i32 s21, s100, -1
	s_cmp_lt_u32 s42, 3
	s_cselect_b32 s42, s42, s21
	s_mulk_i32 s42, 0x6000
	s_add_i32 s42, s53, s42
	s_add_i32 m0, s42, 0x8000
	v_lshl_add_u64 v[66:67], v[160:161], 1, s[40:41]
	global_load_lds_dwordx4 v[66:67], off
	v_lshl_add_u64 v[66:67], v[162:163], 1, s[40:41]
	s_add_i32 m0, s42, 0xa000
	s_lshl_b64 s[28:29], s[28:29], 12
	global_load_lds_dwordx4 v[66:67], off
	s_add_i32 m0, s42, 0xc000
	s_and_b64 s[14:15], s[14:15], exec
	s_cselect_b32 s14, s44, s46
	s_cselect_b32 s15, s45, s47
	s_add_u32 s14, s14, s28
	s_addc_u32 s15, s15, s29
	s_mov_b32 s28, s98
	v_lshl_add_u64 v[66:67], v[168:169], 1, s[40:41]
	s_add_i32 s29, s53, s101
	global_load_lds_dwordx4 v[66:67], off
	v_lshl_add_u64 v[66:67], v[170:171], 1, s[14:15]
	s_mov_b32 m0, s29
	s_mul_i32 s21, s100, 0x6000
	global_load_lds_dwordx4 v[66:67], off
	v_lshl_add_u64 v[66:67], v[172:173], 1, s[14:15]
	s_add_i32 m0, s29, 0x2000
	s_nop 0
	global_load_lds_dwordx4 v[66:67], off
	v_add_u32_e32 v74, s21, v182
	v_add_u32_e32 v75, v74, v181
	ds_read_b128 v[66:69], v75 offset:32768
	v_add_u32_e32 v76, v74, v183
	ds_read_b128 v[70:73], v76 offset:32768
	v_add_u32_e32 v153, v74, v184
	v_add_u32_e32 v155, v74, v185
	v_add_u32_e32 v157, v74, v186
	v_add_u32_e32 v159, v74, v187
	v_add_u32_e32 v209, v74, v188
	v_add_u32_e32 v218, v74, v189
	s_waitcnt lgkmcnt(0)
	v_mfma_f32_32x32x16_bf16 v[82:97], v[66:69], v[142:145], 0
	ds_read_b128 v[66:69], v153 offset:32768
	v_add_u32_e32 v219, v74, v190
	v_add_u32_e32 v220, v74, v191
	v_add_u32_e32 v221, v74, v192
	v_add_u32_e32 v222, v74, v193
	v_mfma_f32_32x32x16_bf16 v[82:97], v[70:73], v[138:141], v[82:97]
	ds_read_b128 v[70:73], v155 offset:32768
	s_waitcnt lgkmcnt(0)
	v_mfma_f32_32x32x16_bf16 v[82:97], v[66:69], v[134:137], v[82:97]
	ds_read_b128 v[66:69], v157 offset:32768
	v_mfma_f32_32x32x16_bf16 v[82:97], v[70:73], v[130:133], v[82:97]
	ds_read_b128 v[70:73], v159 offset:32768
	s_waitcnt lgkmcnt(0)
	v_mfma_f32_32x32x16_bf16 v[82:97], v[66:69], v[126:129], v[82:97]
	ds_read_b128 v[66:69], v209 offset:32768
	v_mfma_f32_32x32x16_bf16 v[82:97], v[70:73], v[122:125], v[82:97]
	ds_read_b128 v[70:73], v218 offset:32768
	s_waitcnt lgkmcnt(0)
	v_mfma_f32_32x32x16_bf16 v[82:97], v[66:69], v[118:121], v[82:97]
	ds_read_b128 v[66:69], v219 offset:32768
	v_mfma_f32_32x32x16_bf16 v[82:97], v[70:73], v[114:117], v[82:97]
	ds_read_b128 v[70:73], v220 offset:32768
	s_waitcnt lgkmcnt(0)
	v_mfma_f32_32x32x16_bf16 v[82:97], v[66:69], v[110:113], v[82:97]
	ds_read_b128 v[66:69], v221 offset:32768
	v_mfma_f32_32x32x16_bf16 v[82:97], v[70:73], v[106:109], v[82:97]
	ds_read_b128 v[70:73], v222 offset:32768
	s_waitcnt lgkmcnt(0)
	v_mfma_f32_32x32x16_bf16 v[82:97], v[66:69], v[102:105], v[82:97]
	v_mfma_f32_32x32x16_bf16 v[82:97], v[70:73], v[98:101], v[82:97]
	ds_read_b128 v[66:69], v75 offset:45056
	ds_read_b128 v[210:213], v76 offset:45056
	s_nop 9
	v_exp_f32_e32 v226, v86
	v_exp_f32_e32 v227, v87
	v_exp_f32_e32 v228, v88
	s_waitcnt lgkmcnt(0)
	v_mfma_f32_32x32x16_bf16 v[66:81], v[66:69], v[142:145], 0
	v_exp_f32_e32 v229, v89
	v_exp_f32_e32 v230, v90
	v_exp_f32_e32 v231, v91
	v_exp_f32_e32 v232, v92
	v_exp_f32_e32 v233, v93
	v_exp_f32_e32 v234, v94
	v_exp_f32_e32 v235, v95
	v_mfma_f32_32x32x16_bf16 v[66:81], v[210:213], v[138:141], v[66:81]
	ds_read_b128 v[210:213], v153 offset:45056
	ds_read_b128 v[214:217], v155 offset:45056
	v_exp_f32_e32 v155, v82
	v_exp_f32_e32 v236, v96
	v_exp_f32_e32 v237, v97
	v_cvt_pk_bf16_f32 v86, v230, v231
	v_cvt_pk_bf16_f32 v87, v232, v233
	v_cvt_pk_bf16_f32 v88, v234, v235
	s_waitcnt lgkmcnt(0)
	v_mfma_f32_32x32x16_bf16 v[66:81], v[210:213], v[134:137], v[66:81]
	v_cvt_pk_bf16_f32 v89, v236, v237
	v_add_u32_e32 v153, s28, v179
	v_permlane32_swap_b32_e32 v86, v88
	v_permlane32_swap_b32_e32 v87, v89
	v_mfma_f32_32x32x16_bf16 v[66:81], v[214:217], v[130:133], v[66:81]
	ds_read_b128 v[210:213], v157 offset:45056
	ds_read_b128 v[214:217], v159 offset:45056
	v_exp_f32_e32 v157, v83
	v_exp_f32_e32 v159, v84
	v_cvt_pk_bf16_f32 v84, v226, v227
	v_cvt_pk_bf16_f32 v82, v155, v157
	s_nop 1
	v_permlane32_swap_b32_e32 v82, v84
	s_waitcnt lgkmcnt(0)
	v_mfma_f32_32x32x16_bf16 v[66:81], v[210:213], v[126:129], v[66:81]
	v_mfma_f32_32x32x16_bf16 v[66:81], v[214:217], v[122:125], v[66:81]
	ds_read_b128 v[210:213], v209 offset:45056
	ds_read_b128 v[214:217], v218 offset:45056
	v_exp_f32_e32 v209, v85
	v_cvt_pk_bf16_f32 v85, v228, v229
	v_cvt_pk_bf16_f32 v83, v159, v209
	s_nop 1
	v_permlane32_swap_b32_e32 v83, v85
	s_waitcnt lgkmcnt(0)
	v_mfma_f32_32x32x16_bf16 v[66:81], v[210:213], v[118:121], v[66:81]
	ds_read_b128 v[210:213], v219 offset:45056
	v_mfma_f32_32x32x16_bf16 v[66:81], v[214:217], v[114:117], v[66:81]
	ds_read_b128 v[214:217], v220 offset:45056
	ds_read_b128 v[218:221], v221 offset:45056
	ds_read_b128 v[222:225], v222 offset:45056
	s_waitcnt lgkmcnt(0)
	v_mfma_f32_32x32x16_bf16 v[66:81], v[210:213], v[110:113], v[66:81]
	v_mfma_f32_32x32x16_bf16 v[66:81], v[214:217], v[106:109], v[66:81]
	v_mfma_f32_32x32x16_bf16 v[66:81], v[218:221], v[102:105], v[66:81]
	v_mfma_f32_32x32x16_bf16 v[66:81], v[222:225], v[98:101], v[66:81]
	ds_read_b64_tr_b16 v[90:91], v153 offset:0
	ds_read_b64_tr_b16 v[92:93], v153 offset:0x800
	ds_read_b64_tr_b16 v[94:95], v153 offset:0x1000
	ds_read_b64_tr_b16 v[96:97], v153 offset:0x1800
	ds_read_b64_tr_b16 v[210:211], v153 offset:0x200
	ds_read_b64_tr_b16 v[212:213], v153 offset:0xa00
	ds_read_b64_tr_b16 v[214:215], v153 offset:0x1200
	ds_read_b64_tr_b16 v[216:217], v153 offset:0x1a00
	s_waitcnt lgkmcnt(4)
	s_nop 0
	v_mfma_f32_32x32x16_bf16 v[2:17], v[82:85], v[90:93], v[2:17]
	s_nop 9
	v_exp_f32_e32 v218, v66
	v_exp_f32_e32 v219, v67
	v_exp_f32_e32 v220, v68
	v_exp_f32_e32 v221, v69
	v_mfma_f32_32x32x16_bf16 v[2:17], v[86:89], v[94:97], v[2:17]
	ds_read_b64_tr_b16 v[66:67], v153 offset:0x400
	ds_read_b64_tr_b16 v[68:69], v153 offset:0xc00
	ds_read_b64_tr_b16 v[90:91], v153 offset:0x1400
	ds_read_b64_tr_b16 v[92:93], v153 offset:0x1c00
	s_waitcnt lgkmcnt(4)
	v_mfma_f32_32x32x16_bf16 v[18:33], v[82:85], v[210:213], v[18:33]
	v_exp_f32_e32 v210, v70
	v_exp_f32_e32 v211, v71
	v_exp_f32_e32 v212, v72
	v_exp_f32_e32 v213, v73
	v_mfma_f32_32x32x16_bf16 v[18:33], v[86:89], v[214:217], v[18:33]
	ds_read_b64_tr_b16 v[70:71], v153 offset:0x600
	ds_read_b64_tr_b16 v[72:73], v153 offset:0xe00
	ds_read_b64_tr_b16 v[94:95], v153 offset:0x1600
	ds_read_b64_tr_b16 v[96:97], v153 offset:0x1e00
	s_waitcnt lgkmcnt(4)
	v_mfma_f32_32x32x16_bf16 v[34:49], v[82:85], v[66:69], v[34:49]
	v_exp_f32_e32 v214, v74
	v_exp_f32_e32 v215, v75
	v_exp_f32_e32 v216, v76
	v_exp_f32_e32 v217, v77
	v_mfma_f32_32x32x16_bf16 v[34:49], v[86:89], v[90:93], v[34:49]
	ds_read_b64_tr_b16 v[66:67], v153 offset:0x2000
	ds_read_b64_tr_b16 v[68:69], v153 offset:0x2800
	ds_read_b64_tr_b16 v[74:75], v153 offset:0x3000
	ds_read_b64_tr_b16 v[76:77], v153 offset:0x3800
	s_waitcnt lgkmcnt(4)
	v_exp_f32_e32 v90, v78
	v_mfma_f32_32x32x16_bf16 v[50:65], v[82:85], v[70:73], v[50:65]
	v_exp_f32_e32 v91, v79
	v_cvt_pk_bf16_f32 v72, v210, v211
	v_cvt_pk_bf16_f32 v73, v212, v213
	v_mfma_f32_32x32x16_bf16 v[50:65], v[86:89], v[94:97], v[50:65]
	v_exp_f32_e32 v92, v80
	v_exp_f32_e32 v248, v81
	v_cvt_pk_bf16_f32 v78, v214, v215
	v_cvt_pk_bf16_f32 v79, v216, v217
	v_cvt_pk_bf16_f32 v80, v90, v91
	v_cvt_pk_bf16_f32 v70, v218, v219
	v_cvt_pk_bf16_f32 v71, v220, v221
	v_permlane32_swap_b32_e32 v78, v80
	v_cvt_pk_bf16_f32 v81, v92, v248
	v_permlane32_swap_b32_e32 v70, v72
	v_permlane32_swap_b32_e32 v71, v73
	s_nop 0
	v_permlane32_swap_b32_e32 v79, v81
	ds_read_b64_tr_b16 v[82:83], v153 offset:0x2200
	ds_read_b64_tr_b16 v[84:85], v153 offset:0x2a00
	ds_read_b64_tr_b16 v[86:87], v153 offset:0x3200
	ds_read_b64_tr_b16 v[88:89], v153 offset:0x3a00
	s_waitcnt lgkmcnt(4)
	s_nop 0
	v_mfma_f32_32x32x16_bf16 v[2:17], v[70:73], v[66:69], v[2:17]
	v_add_f32_e32 v246, v155, v157
	v_add_f32_e32 v247, v218, v219
	v_add_f32_e32 v246, v246, v159
	v_add_f32_e32 v247, v247, v220
	v_mfma_f32_32x32x16_bf16 v[2:17], v[78:81], v[74:77], v[2:17]
	v_add_f32_e32 v246, v246, v209
	v_add_f32_e32 v247, v247, v221
	v_add_f32_e32 v246, v246, v226
	v_add_f32_e32 v247, v247, v210
	ds_read_b64_tr_b16 v[66:67], v153 offset:0x2400
	ds_read_b64_tr_b16 v[68:69], v153 offset:0x2c00
	ds_read_b64_tr_b16 v[74:75], v153 offset:0x3400
	ds_read_b64_tr_b16 v[76:77], v153 offset:0x3c00
	s_waitcnt lgkmcnt(4)
	v_mfma_f32_32x32x16_bf16 v[18:33], v[70:73], v[82:85], v[18:33]
	v_add_f32_e32 v246, v246, v227
	v_add_f32_e32 v247, v247, v211
	v_add_f32_e32 v246, v246, v228
	v_add_f32_e32 v247, v247, v212
	v_mfma_f32_32x32x16_bf16 v[18:33], v[78:81], v[86:89], v[18:33]
	v_add_f32_e32 v246, v246, v229
	v_add_f32_e32 v247, v247, v213
	v_add_f32_e32 v246, v246, v230
	v_add_f32_e32 v247, v247, v214
	ds_read_b64_tr_b16 v[82:83], v153 offset:0x2600
	ds_read_b64_tr_b16 v[84:85], v153 offset:0x2e00
	ds_read_b64_tr_b16 v[86:87], v153 offset:0x3600
	ds_read_b64_tr_b16 v[88:89], v153 offset:0x3e00
	s_waitcnt lgkmcnt(4)
	v_mfma_f32_32x32x16_bf16 v[34:49], v[70:73], v[66:69], v[34:49]
	v_add_f32_e32 v246, v246, v231
	v_add_f32_e32 v247, v247, v215
	v_add_f32_e32 v246, v246, v232
	v_add_f32_e32 v247, v247, v216
	v_mfma_f32_32x32x16_bf16 v[34:49], v[78:81], v[74:77], v[34:49]
	v_add_f32_e32 v246, v246, v233
	v_add_f32_e32 v247, v247, v217
	v_add_f32_e32 v246, v246, v234
	v_add_f32_e32 v247, v247, v90
	s_waitcnt lgkmcnt(0)
	v_mfma_f32_32x32x16_bf16 v[50:65], v[70:73], v[82:85], v[50:65]
	v_add_f32_e32 v246, v246, v235
	v_add_f32_e32 v247, v247, v91
	v_add_f32_e32 v246, v246, v236
	v_add_f32_e32 v247, v247, v92
	v_add_f32_e32 v246, v246, v237
	v_add_f32_e32 v247, v247, v248
	v_add_f32_e32 v246, v246, v247
	v_mov_b32_e32 v247, v246
	s_nop 1
	v_permlane32_swap_b32_e32 v246, v247
	v_add_f32_e32 v246, v246, v247
	v_add_f32_e32 v151, v151, v246
	s_waitcnt vmcnt(5)
	s_add_u32 s0, s0, 64
	s_addc_u32 s1, s1, 0
	s_add_i32 s4, s4, 1
	s_mov_b32 s21, s98
	s_mov_b32 s98, s99
	s_mov_b32 s99, s101
	s_mov_b32 s101, s21
	s_add_i32 s100, s100, 1
	s_cmp_eq_u32 s100, 3
	s_cselect_b32 s100, 0, s100
	s_cmpk_eq_i32 s0, 0x4140
	s_waitcnt vmcnt(5)
	s_barrier
	v_mfma_f32_32x32x16_bf16 v[50:65], v[78:81], v[86:89], v[50:65]
	s_cbranch_scc0 .LBB0_2312
	s_lshl_b32 s0, s52, 2
	s_add_i32 s4, s0, 0
	s_add_i32 s4, s4, 0x1e000
	ds_read_b128 v[66:69], v196
	ds_read_b128 v[70:73], v197
	s_waitcnt lgkmcnt(1)
	v_mfma_f32_32x32x16_bf16 v[82:97], v[66:69], v[142:145], 0
	s_waitcnt lgkmcnt(0)
	v_mfma_f32_32x32x16_bf16 v[82:97], v[70:73], v[138:141], v[82:97]
	ds_read_b128 v[66:69], v198
	ds_read_b128 v[70:73], v199
	s_waitcnt lgkmcnt(1)
	v_mfma_f32_32x32x16_bf16 v[82:97], v[66:69], v[134:137], v[82:97]
	s_waitcnt lgkmcnt(0)
	v_mfma_f32_32x32x16_bf16 v[82:97], v[70:73], v[130:133], v[82:97]
	ds_read_b128 v[66:69], v200
	ds_read_b128 v[70:73], v201
	s_waitcnt lgkmcnt(1)
	v_mfma_f32_32x32x16_bf16 v[82:97], v[66:69], v[126:129], v[82:97]
	s_waitcnt lgkmcnt(0)
	v_mfma_f32_32x32x16_bf16 v[82:97], v[70:73], v[122:125], v[82:97]
	ds_read_b128 v[66:69], v202
	ds_read_b128 v[70:73], v203
	s_waitcnt lgkmcnt(1)
	v_mfma_f32_32x32x16_bf16 v[82:97], v[66:69], v[118:121], v[82:97]
	s_waitcnt lgkmcnt(0)
	v_mfma_f32_32x32x16_bf16 v[82:97], v[70:73], v[114:117], v[82:97]
	ds_read_b128 v[66:69], v204
	ds_read_b128 v[70:73], v205
	s_waitcnt lgkmcnt(1)
	v_mfma_f32_32x32x16_bf16 v[82:97], v[66:69], v[110:113], v[82:97]
	s_waitcnt lgkmcnt(0)
	v_mfma_f32_32x32x16_bf16 v[82:97], v[70:73], v[106:109], v[82:97]
	ds_read_b128 v[66:69], v206
	ds_read_b128 v[70:73], v207
	s_waitcnt lgkmcnt(1)
	v_mfma_f32_32x32x16_bf16 v[82:97], v[66:69], v[102:105], v[82:97]
	s_waitcnt lgkmcnt(0)
	v_mfma_f32_32x32x16_bf16 v[82:97], v[70:73], v[98:101], v[82:97]
	ds_read_b128 v[66:69], v196 offset:12288
	ds_read_b128 v[160:163], v197 offset:12288
	s_waitcnt lgkmcnt(1)
	v_mfma_f32_32x32x16_bf16 v[66:81], v[66:69], v[142:145], 0
	s_waitcnt lgkmcnt(0)
	v_mfma_f32_32x32x16_bf16 v[66:81], v[160:163], v[138:141], v[66:81]
	ds_read_b128 v[138:141], v198 offset:12288
	ds_read_b128 v[142:145], v199 offset:12288
	s_waitcnt lgkmcnt(1)
	v_mfma_f32_32x32x16_bf16 v[66:81], v[138:141], v[134:137], v[66:81]
	s_waitcnt lgkmcnt(0)
	v_mfma_f32_32x32x16_bf16 v[66:81], v[142:145], v[130:133], v[66:81]
	ds_read_b128 v[130:133], v200 offset:12288
	ds_read_b128 v[134:137], v201 offset:12288
	s_waitcnt lgkmcnt(1)
	v_mfma_f32_32x32x16_bf16 v[66:81], v[130:133], v[126:129], v[66:81]
	v_exp_f32_e32 v130, v82
	v_exp_f32_e32 v131, v83
	v_exp_f32_e32 v132, v84
	v_cvt_pk_bf16_f32 v82, v130, v131
	s_waitcnt lgkmcnt(0)
	v_mfma_f32_32x32x16_bf16 v[66:81], v[134:137], v[122:125], v[66:81]
	ds_read_b128 v[122:125], v202 offset:12288
	ds_read_b128 v[126:129], v203 offset:12288
	s_waitcnt lgkmcnt(1)
	v_mfma_f32_32x32x16_bf16 v[66:81], v[122:125], v[118:121], v[66:81]
	s_waitcnt lgkmcnt(0)
	v_mfma_f32_32x32x16_bf16 v[66:81], v[126:129], v[114:117], v[66:81]
	ds_read_b128 v[114:117], v204 offset:12288
	ds_read_b128 v[118:121], v205 offset:12288
	ds_read_b128 v[122:125], v206 offset:12288
	ds_read_b128 v[126:129], v207 offset:12288
	s_waitcnt lgkmcnt(3)
	v_mfma_f32_32x32x16_bf16 v[66:81], v[114:117], v[110:113], v[66:81]
	v_exp_f32_e32 v110, v85
	v_exp_f32_e32 v111, v86
	v_exp_f32_e32 v112, v87
	v_exp_f32_e32 v113, v88
	v_exp_f32_e32 v114, v89
	v_exp_f32_e32 v115, v90
	v_exp_f32_e32 v116, v91
	s_waitcnt lgkmcnt(2)
	v_mfma_f32_32x32x16_bf16 v[66:81], v[118:121], v[106:109], v[66:81]
	v_exp_f32_e32 v106, v92
	v_exp_f32_e32 v107, v93
	v_exp_f32_e32 v108, v94
	v_exp_f32_e32 v109, v95
	v_exp_f32_e32 v117, v96
	v_exp_f32_e32 v118, v97
	v_cvt_pk_bf16_f32 v83, v132, v110
	s_waitcnt lgkmcnt(1)
	v_mfma_f32_32x32x16_bf16 v[66:81], v[122:125], v[102:105], v[66:81]
	v_cvt_pk_bf16_f32 v84, v111, v112
	v_cvt_pk_bf16_f32 v85, v113, v114
	v_cvt_pk_bf16_f32 v86, v115, v116
	v_cvt_pk_bf16_f32 v87, v106, v107
	v_cvt_pk_bf16_f32 v88, v108, v109
	v_cvt_pk_bf16_f32 v89, v117, v118
	v_permlane32_swap_b32_e32 v82, v84
	s_waitcnt lgkmcnt(0)
	v_mfma_f32_32x32x16_bf16 v[66:81], v[126:129], v[98:101], v[66:81]
	v_permlane32_swap_b32_e32 v83, v85
	v_permlane32_swap_b32_e32 v86, v88
	v_permlane32_swap_b32_e32 v87, v89
	ds_read_b64_tr_b16 v[90:91], v208 offset:0
	ds_read_b64_tr_b16 v[92:93], v208 offset:0x800
	ds_read_b64_tr_b16 v[94:95], v208 offset:0x1000
	ds_read_b64_tr_b16 v[96:97], v208 offset:0x1800
	ds_read_b64_tr_b16 v[98:99], v208 offset:0x200
	ds_read_b64_tr_b16 v[100:101], v208 offset:0xa00
	ds_read_b64_tr_b16 v[102:103], v208 offset:0x1200
	ds_read_b64_tr_b16 v[104:105], v208 offset:0x1a00
	s_waitcnt lgkmcnt(4)
	s_nop 0
	v_mfma_f32_32x32x16_bf16 v[2:17], v[82:85], v[90:93], v[2:17]
	s_nop 6
	v_exp_f32_e32 v119, v66
	v_exp_f32_e32 v120, v67
	v_exp_f32_e32 v121, v68
	v_exp_f32_e32 v122, v69
	v_mfma_f32_32x32x16_bf16 v[2:17], v[86:89], v[94:97], v[2:17]
	ds_read_b64_tr_b16 v[66:67], v208 offset:0x400
	ds_read_b64_tr_b16 v[68:69], v208 offset:0xc00
	ds_read_b64_tr_b16 v[90:91], v208 offset:0x1400
	ds_read_b64_tr_b16 v[92:93], v208 offset:0x1c00
	s_waitcnt lgkmcnt(4)
	v_mfma_f32_32x32x16_bf16 v[18:33], v[82:85], v[98:101], v[18:33]
	v_exp_f32_e32 v98, v70
	v_exp_f32_e32 v99, v71
	v_exp_f32_e32 v100, v72
	v_exp_f32_e32 v101, v73
	v_mfma_f32_32x32x16_bf16 v[18:33], v[86:89], v[102:105], v[18:33]
	ds_read_b64_tr_b16 v[70:71], v208 offset:0x600
	ds_read_b64_tr_b16 v[72:73], v208 offset:0xe00
	ds_read_b64_tr_b16 v[94:95], v208 offset:0x1600
	ds_read_b64_tr_b16 v[96:97], v208 offset:0x1e00
	s_waitcnt lgkmcnt(4)
	v_mfma_f32_32x32x16_bf16 v[34:49], v[82:85], v[66:69], v[34:49]
	v_exp_f32_e32 v102, v74
	v_exp_f32_e32 v103, v75
	v_exp_f32_e32 v104, v76
	v_exp_f32_e32 v105, v77
	v_mfma_f32_32x32x16_bf16 v[34:49], v[86:89], v[90:93], v[34:49]
	ds_read_b64_tr_b16 v[74:75], v208 offset:0x2000
	ds_read_b64_tr_b16 v[76:77], v208 offset:0x2800
	ds_read_b64_tr_b16 v[90:91], v208 offset:0x3000
	ds_read_b64_tr_b16 v[92:93], v208 offset:0x3800
	s_waitcnt lgkmcnt(4)
	v_add_f32_e32 v66, v130, v131
	v_add_f32_e32 v67, v119, v120
	v_mfma_f32_32x32x16_bf16 v[50:65], v[82:85], v[70:73], v[50:65]
	v_add_f32_e32 v66, v66, v132
	v_add_f32_e32 v67, v67, v121
	v_exp_f32_e32 v123, v78
	v_add_f32_e32 v66, v66, v110
	v_add_f32_e32 v67, v67, v122
	v_exp_f32_e32 v124, v79
	v_add_f32_e32 v66, v66, v111
	v_add_f32_e32 v67, v67, v98
	v_mfma_f32_32x32x16_bf16 v[50:65], v[86:89], v[94:97], v[50:65]
	v_add_f32_e32 v66, v66, v112
	v_add_f32_e32 v67, v67, v99
	v_exp_f32_e32 v125, v80
	v_add_f32_e32 v66, v66, v113
	v_add_f32_e32 v67, v67, v100
	v_exp_f32_e32 v81, v81
	v_add_f32_e32 v66, v66, v114
	v_add_f32_e32 v67, v67, v101
	v_cvt_pk_bf16_f32 v68, v119, v120
	v_add_f32_e32 v66, v66, v115
	v_add_f32_e32 v67, v67, v102
	v_cvt_pk_bf16_f32 v69, v121, v122
	v_add_f32_e32 v66, v66, v116
	v_add_f32_e32 v67, v67, v103
	v_cvt_pk_bf16_f32 v70, v98, v99
	v_add_f32_e32 v66, v66, v106
	v_add_f32_e32 v67, v67, v104
	v_cvt_pk_bf16_f32 v71, v100, v101
	v_add_f32_e32 v66, v66, v107
	v_add_f32_e32 v67, v67, v105
	v_cvt_pk_bf16_f32 v78, v102, v103
	v_add_f32_e32 v66, v66, v108
	v_add_f32_e32 v67, v67, v123
	v_cvt_pk_bf16_f32 v79, v104, v105
	v_add_f32_e32 v66, v66, v109
	v_add_f32_e32 v67, v67, v124
	v_cvt_pk_bf16_f32 v80, v123, v124
	v_add_f32_e32 v66, v66, v117
	v_add_f32_e32 v67, v67, v125
	v_permlane32_swap_b32_e32 v68, v70
	v_add_f32_e32 v66, v66, v118
	v_add_f32_e32 v67, v67, v81
	v_cvt_pk_bf16_f32 v81, v125, v81
	v_add_f32_e32 v66, v66, v67
	v_mov_b32_e32 v67, v66
	s_nop 1
	v_permlane32_swap_b32_e32 v66, v67
	v_permlane32_swap_b32_e32 v69, v71
	v_permlane32_swap_b32_e32 v78, v80
	v_permlane32_swap_b32_e32 v79, v81
	ds_read_b64_tr_b16 v[82:83], v208 offset:0x2200
	ds_read_b64_tr_b16 v[84:85], v208 offset:0x2a00
	ds_read_b64_tr_b16 v[86:87], v208 offset:0x3200
	ds_read_b64_tr_b16 v[88:89], v208 offset:0x3a00
	s_waitcnt lgkmcnt(4)
	v_mfma_f32_32x32x16_bf16 v[2:17], v[68:71], v[74:77], v[2:17]
	s_nop 0
	v_mfma_f32_32x32x16_bf16 v[2:17], v[78:81], v[90:93], v[2:17]
	ds_read_b64_tr_b16 v[72:73], v208 offset:0x2400
	ds_read_b64_tr_b16 v[74:75], v208 offset:0x2c00
	ds_read_b64_tr_b16 v[90:91], v208 offset:0x3400
	ds_read_b64_tr_b16 v[92:93], v208 offset:0x3c00
	s_waitcnt lgkmcnt(4)
	v_mfma_f32_32x32x16_bf16 v[18:33], v[68:71], v[82:85], v[18:33]
	v_mfma_f32_32x32x16_bf16 v[18:33], v[78:81], v[86:89], v[18:33]
	ds_read_b64_tr_b16 v[82:83], v208 offset:0x2600
	ds_read_b64_tr_b16 v[84:85], v208 offset:0x2e00
	ds_read_b64_tr_b16 v[86:87], v208 offset:0x3600
	ds_read_b64_tr_b16 v[88:89], v208 offset:0x3e00
	s_waitcnt lgkmcnt(4)
	v_mfma_f32_32x32x16_bf16 v[34:49], v[68:71], v[72:75], v[34:49]
	v_mfma_f32_32x32x16_bf16 v[34:49], v[78:81], v[90:93], v[34:49]
	s_waitcnt lgkmcnt(0)
	v_mfma_f32_32x32x16_bf16 v[50:65], v[68:71], v[82:85], v[50:65]
	s_waitcnt vmcnt(0)
	s_barrier
	v_mfma_f32_32x32x16_bf16 v[50:65], v[78:81], v[86:89], v[50:65]
	s_and_saveexec_b64 s[0:1], s[2:3]
	s_cbranch_execz .LBB0_2310
	v_add_f32_e32 v66, v66, v67
	v_lshl_add_u32 v68, v165, 2, s4
	v_add_f32_e32 v66, v151, v66
	ds_write_b32 v68, v66
	s_branch .LBB0_2310
